# in-proj GEMM moved to the 3-stage direct-to-LDS ring; its epilogue LDS staging relocated per item into the ring stage freed by the last k-tile (one extra workgroup barrier before the epilogue)
# speedup vs baseline: 1.1059x; 1.0155x over previous
.LBB0_968:
	s_add_u32 s20, s76, 0x12000
	s_addc_u32 s21, s77, 0
	s_add_u32 s0, s76, 0x3900000
	s_addc_u32 s1, s77, 0
	v_writelane_b32 v251, s0, 38
	v_mbcnt_hi_u32_b32 v206, -1, v171
	v_and_b32_e32 v171, 64, v206
	v_writelane_b32 v251, s1, 39
	s_add_u32 s0, s76, 0x5900000
	s_addc_u32 s1, s77, 0
	v_writelane_b32 v252, s0, 31
	s_waitcnt vmcnt(3)
	v_mov_b32_e32 v1, 0
	v_mov_b32_e32 v203, 0x358637bd
	v_writelane_b32 v252, s1, 32
	s_add_u32 s0, s76, 0x7a00000
	s_addc_u32 s1, s77, 0
	v_writelane_b32 v252, s0, 33
	v_mov_b32_e32 v204, 1
	v_add_u32_e32 v207, 64, v171
	v_writelane_b32 v252, s1, 34
	s_add_u32 s0, s76, 0x9b00000
	s_addc_u32 s1, s77, 0
	v_writelane_b32 v252, s0, 26
	v_xor_b32_e32 v213, 32, v206
	v_xor_b32_e32 v212, 16, v206
	v_writelane_b32 v252, s1, 27
	s_add_u32 s0, s76, 0xab00000
	s_addc_u32 s1, s77, 0
	v_writelane_b32 v251, s0, 2
	s_add_u32 s2, s76, 0xeb00000
	s_addc_u32 s3, s77, 0
	v_writelane_b32 v251, s1, 3
	s_mul_i32 s0, s79, s78
	v_readlane_b32 s4, v251, 22
	v_readlane_b32 s12, v251, 30
	v_readlane_b32 s13, v251, 31
	v_readlane_b32 s14, v251, 32
	v_readlane_b32 s15, v251, 33
	v_readlane_b32 s16, v251, 34
	v_readlane_b32 s17, v251, 35
	v_readlane_b32 s18, v251, 36
	v_readlane_b32 s19, v251, 37
	s_mov_b64 s[12:13], s[16:17]
	s_mov_b64 s[14:15], s[18:19]
	s_mov_b64 s[18:19], s[2:3]
	s_add_u32 s2, s12, 0x1000
	s_addc_u32 s3, s13, 0
	s_add_i32 s1, s57, 0x20ff
	s_add_u32 s30, s76, 0x80200
	s_addc_u32 s31, s77, 0
	s_add_u32 s40, s76, 0x80400
	s_addc_u32 s41, s77, 0
	s_add_u32 s42, s76, 0x80500
	s_addc_u32 s43, s77, 0
	s_add_u32 s44, s76, 0x80600
	s_addc_u32 s45, s77, 0
	s_add_u32 s46, s76, 0x80700
	s_addc_u32 s47, s77, 0
	s_add_u32 s48, s76, 0x80800
	s_addc_u32 s49, s77, 0
	s_add_u32 s52, s76, 0x80900
	s_addc_u32 s53, s77, 0
	s_add_u32 s68, s76, 0x80a00
	s_addc_u32 s69, s77, 0
	s_add_u32 s70, s76, 0x80b00
	s_addc_u32 s71, s77, 0
	s_add_u32 s72, s76, 0x80c00
	s_addc_u32 s73, s77, 0
	s_add_u32 s80, s76, 0x80d00
	s_addc_u32 s81, s77, 0
	s_add_u32 s84, s76, 0x80e00
	s_addc_u32 s85, s77, 0
	s_add_u32 s86, s76, 0x80f00
	s_addc_u32 s87, s77, 0
	s_add_u32 s90, s76, 0x81000
	s_addc_u32 s91, s77, 0
	s_add_u32 s92, s76, 0x81100
	s_addc_u32 s93, s77, 0
	s_add_u32 s94, s76, 0x81200
	v_writelane_b32 v252, s2, 35
	s_addc_u32 s95, s77, 0
	s_add_u32 s96, s76, 0x81300
	v_writelane_b32 v252, s3, 36
	v_readlane_b32 s2, v251, 0
	s_mul_i32 s27, s0, s2
	s_addc_u32 s97, s77, 0
	v_readlane_b32 s0, v251, 20
	s_cmp_eq_u32 s0, 15
	s_cselect_b64 s[2:3], -1, 0
	v_writelane_b32 v252, s2, 37
	s_cmp_eq_u32 s0, 14
	v_readlane_b32 s5, v251, 23
	v_writelane_b32 v252, s3, 38
	s_cselect_b64 s[2:3], -1, 0
	v_writelane_b32 v252, s2, 39
	s_cmp_eq_u32 s0, 13
	v_xor_b32_e32 v211, 8, v206
	v_writelane_b32 v252, s3, 40
	s_cselect_b64 s[2:3], -1, 0
	v_writelane_b32 v252, s2, 41
	s_cmp_eq_u32 s0, 12
	v_xor_b32_e32 v210, 4, v206
	v_writelane_b32 v252, s3, 42
	s_cselect_b64 s[2:3], -1, 0
	v_writelane_b32 v252, s2, 43
	s_cmp_eq_u32 s0, 11
	v_xor_b32_e32 v209, 2, v206
	v_writelane_b32 v252, s3, 44
	s_cselect_b64 s[2:3], -1, 0
	v_writelane_b32 v252, s2, 45
	s_cmp_eq_u32 s0, 10
	v_xor_b32_e32 v208, 1, v206
	v_writelane_b32 v252, s3, 46
	s_cselect_b64 s[2:3], -1, 0
	v_writelane_b32 v252, s2, 47
	s_cmp_eq_u32 s0, 9
	v_mov_b32_e32 v205, 0x437f0000
	v_writelane_b32 v252, s3, 48
	s_cselect_b64 s[2:3], -1, 0
	v_writelane_b32 v252, s2, 49
	s_cmp_eq_u32 s0, 8
	v_mov_b32_e32 v214, 0x4607fc00
	v_writelane_b32 v252, s3, 50
	s_cselect_b64 s[2:3], -1, 0
	v_writelane_b32 v252, s2, 51
	s_cmp_eq_u32 s0, 7
	v_mov_b32_e32 v215, 0xffffe000
	v_writelane_b32 v252, s3, 52
	s_cselect_b64 s[2:3], -1, 0
	v_writelane_b32 v252, s2, 53
	s_cmp_eq_u32 s0, 6
	v_mov_b32_e32 v216, 0x100
	v_writelane_b32 v252, s3, 54
	s_cselect_b64 s[2:3], -1, 0
	v_writelane_b32 v252, s2, 55
	s_cmp_eq_u32 s0, 5
	v_mov_b32_e32 v217, 0x7c
	v_writelane_b32 v252, s3, 56
	s_cselect_b64 s[2:3], -1, 0
	v_writelane_b32 v252, s2, 57
	s_cmp_eq_u32 s0, 4
	v_mov_b32_e32 v218, 0x42800000
	v_writelane_b32 v252, s3, 58
	s_cselect_b64 s[2:3], -1, 0
	v_writelane_b32 v252, s2, 59
	s_cmp_eq_u32 s0, 3
	v_not_b32_e32 v219, 63
	v_writelane_b32 v252, s3, 60
	s_cselect_b64 s[2:3], -1, 0
	v_writelane_b32 v252, s2, 61
	s_cmp_eq_u32 s0, 2
	s_movk_i32 s50, 0x2000
	v_writelane_b32 v252, s3, 62
	s_cselect_b64 s[2:3], -1, 0
	v_writelane_b32 v252, s2, 63
	s_cmp_eq_u32 s0, 1
	v_writelane_b32 v252, s18, 24
	v_writelane_b32 v253, s3, 0
	s_cselect_b64 s[2:3], -1, 0
	v_writelane_b32 v253, s2, 1
	s_cmp_eq_u32 s0, 0
	s_mov_b32 s63, 0x800000
	v_writelane_b32 v253, s3, 2
	s_cselect_b64 s[2:3], -1, 0
	v_writelane_b32 v253, s2, 3
	s_lshl_b32 s0, s0, 8
	s_movk_i32 s33, 0x7fff
	v_writelane_b32 v253, s3, 4
	v_readlane_b32 s2, v251, 18
	v_readlane_b32 s3, v251, 19
	s_add_u32 s0, s2, s0
	s_addc_u32 s2, s3, 0
	s_add_u32 s4, s0, 0x1400
	s_addc_u32 s5, s2, 0
	s_add_u32 s34, s0, 0x2400
	s_addc_u32 s35, s2, 0
	s_add_u32 s2, s76, 0x83400
	v_writelane_b32 v253, s4, 5
	s_addc_u32 s3, s77, 0
	s_add_u32 s38, s76, 0x83500
	v_writelane_b32 v253, s5, 6
	v_writelane_b32 v253, s2, 7
	s_addc_u32 s39, s77, 0
	s_addk_i32 s28, 0x840
	v_writelane_b32 v253, s3, 8
	s_lshr_b32 s0, s28, 3
	s_mul_i32 s2, s56, 0x108
	s_sub_i32 s0, s0, s2
	s_cmp_lt_i32 s62, s0
	v_writelane_b32 v253, s0, 9
	s_cselect_b64 s[2:3], -1, 0
	v_writelane_b32 v253, s2, 10
	s_add_i32 s0, 16, 0x18000
	s_cmpk_lt_i32 s64, 0x200
	v_writelane_b32 v253, s3, 11
	v_writelane_b32 v253, s0, 12
	s_cselect_b64 s[2:3], -1, 0
	v_writelane_b32 v253, s2, 13
	s_cmpk_lt_i32 s64, 0x400
	s_mov_b64 s[28:29], s[20:21]
	v_writelane_b32 v253, s3, 14
	s_cselect_b64 s[2:3], -1, 0
	s_lshl_b32 s20, s56, 5
	v_writelane_b32 v253, s2, 15
	s_cmpk_lt_u32 s64, 0x100
	v_mov_b32_e32 v0, s0
	v_writelane_b32 v253, s3, 16
	s_cselect_b64 s[2:3], -1, 0
	v_writelane_b32 v253, s2, 17
	s_movk_i32 s0, 0x1200
	v_mad_u32_u24 v202, v222, s0, v0
	s_nop 1
	v_readfirstlane_b32 s98, v202
	s_nop 1
	v_writelane_b32 v250, s98, 7
	v_writelane_b32 v253, s3, 18
	s_add_u32 s2, s76, 0x1400000
	s_addc_u32 s3, s77, 0
	v_writelane_b32 v253, s2, 19
	s_sub_i32 s0, 0xffffdf01, s57
	s_max_i32 s0, s1, s0
	v_writelane_b32 v253, s3, 20
	v_readlane_b32 s2, v251, 62
	s_mul_hi_u32 s2, s0, s2
	v_readlane_b32 s5, v251, 63
	s_mul_i32 s3, s2, s5
	s_sub_i32 s0, s0, s3
	s_ashr_i32 s1, s1, 31
	v_readlane_b32 s3, v251, 61
	s_xor_b32 s1, s1, s3
	s_add_i32 s3, s2, 1
	s_sub_i32 s4, s0, s5
	s_cmp_ge_u32 s0, s5
	s_cselect_b32 s2, s3, s2
	s_cselect_b32 s0, s4, s0
	s_add_i32 s3, s2, 1
	s_cmp_ge_u32 s0, s5
	s_cselect_b32 s0, s3, s2
	s_xor_b32 s0, s0, s1
	s_sub_i32 s0, s0, s1
	v_writelane_b32 v253, s0, 21
	s_mul_i32 s0, s56, 0x420
	s_lshl_b32 s1, s62, 2
	s_add_i32 s0, s0, s1
	s_lshl_b32 s1, s62, 7
	v_writelane_b32 v253, s0, 22
	s_add_i32 s0, s36, s1
	v_writelane_b32 v253, s0, 23
	s_lshl_b32 s0, s56, 12
	v_writelane_b32 v253, s1, 24
	s_add_i32 s0, s0, s1
	v_writelane_b32 v253, s0, 25
	s_lshl_b32 s0, s56, 10
	s_lshl_b32 s1, s62, 5
	v_writelane_b32 v253, s1, 26
	s_add_i32 s0, s0, s1
	v_writelane_b32 v253, s0, 27
	s_lshl_b32 s0, s51, 2
	v_writelane_b32 v253, s0, 28
	s_add_i32 s0, 16, 0x1b000
	v_writelane_b32 v253, s0, 29
	v_writelane_b32 v253, s66, 30
	s_lshl_b32 s36, s51, 7
	s_lshl_b32 s37, s51, 5
	v_writelane_b32 v253, s67, 31
	v_writelane_b32 v253, s60, 32
	s_mov_b32 s79, 0x20000
	s_mov_b32 s89, 0x11000
	v_writelane_b32 v253, s61, 33
	v_writelane_b32 v253, s30, 34
	s_movk_i32 s88, 0x4200
	s_mov_b32 s17, 0
	v_writelane_b32 v253, s31, 35
	v_writelane_b32 v253, s34, 36
	s_mov_b32 s83, 0
	s_mov_b64 s[4:5], -1
	v_writelane_b32 v253, s35, 37
	v_writelane_b32 v253, s38, 38
	s_mov_b64 s[74:75], 0x100
	v_writelane_b32 v252, s19, 25
	v_writelane_b32 v253, s39, 39
	v_writelane_b32 v253, s27, 40
	v_writelane_b32 v253, s40, 41
	v_readlane_b32 s6, v251, 24
	v_readlane_b32 s7, v251, 25
	v_writelane_b32 v253, s41, 42
	v_writelane_b32 v253, s42, 43
	v_readlane_b32 s8, v251, 26
	v_readlane_b32 s9, v251, 27
	v_writelane_b32 v253, s43, 44
	v_writelane_b32 v253, s44, 45
	v_readlane_b32 s10, v251, 28
	v_readlane_b32 s11, v251, 29
	v_writelane_b32 v253, s45, 46
	v_writelane_b32 v253, s46, 47
	s_nop 1
	v_writelane_b32 v253, s47, 48
	v_writelane_b32 v253, s48, 49
	s_nop 1
	v_writelane_b32 v253, s49, 50
	v_writelane_b32 v253, s52, 51
	s_nop 1
	v_writelane_b32 v253, s53, 52
	v_writelane_b32 v253, s68, 53
	s_nop 1
	v_writelane_b32 v253, s69, 54
	v_writelane_b32 v253, s70, 55
	s_nop 1
	v_writelane_b32 v253, s71, 56
	v_writelane_b32 v253, s72, 57
	s_nop 1
	v_writelane_b32 v253, s73, 58
	v_writelane_b32 v253, s80, 59
	s_nop 1
	v_writelane_b32 v253, s81, 60
	v_writelane_b32 v253, s84, 61
	s_nop 1
	v_writelane_b32 v253, s85, 62
	v_writelane_b32 v253, s86, 63
	s_nop 1
	v_writelane_b32 v254, s87, 0
	v_writelane_b32 v254, s90, 1
	s_nop 1
	v_writelane_b32 v254, s91, 2
	v_writelane_b32 v254, s92, 3
	s_nop 1
	v_writelane_b32 v254, s93, 4
	v_writelane_b32 v254, s94, 5
	s_nop 1
	v_writelane_b32 v254, s95, 6
	v_writelane_b32 v254, s96, 7
	s_nop 1
	v_writelane_b32 v254, s97, 8
	v_writelane_b32 v254, s28, 9
	s_nop 1
	v_writelane_b32 v254, s29, 10
	v_writelane_b32 v254, s36, 11
	v_writelane_b32 v254, s37, 12
	v_writelane_b32 v254, s20, 13
	s_branch .LBB0_971

.LBB0_1032:
	s_or_b64 exec, exec, s[0:1]
	v_readlane_b32 s0, v253, 10
	v_readlane_b32 s1, v253, 11
	s_waitcnt lgkmcnt(0)
	v_mov_b32_e32 v2, v170
	s_andn2_b64 vcc, exec, s[0:1]
	v_writelane_b32 v254, s17, 16
	s_barrier
	s_cbranch_vccnz .LBB0_1102
	v_lshlrev_b32_e32 v0, 4, v2
	v_readlane_b32 s0, v252, 13
	v_and_b32_e32 v0, 0x70, v0
	v_readlane_b32 s1, v252, 14
	s_waitcnt vmcnt(7)
	v_and_b32_e32 v4, 15, v2
	v_ashrrev_i32_e32 v221, 3, v2
	v_lshl_add_u64 v[168:169], s[0:1], 0, v[0:1]
	v_readlane_b32 s0, v251, 54
	v_readlane_b32 s1, v251, 55
	v_bfe_u32 v5, v2, 6, 1
	v_ashrrev_i32_e32 v6, 7, v2
	v_lshl_add_u64 v[172:173], s[0:1], 0, v[0:1]
	v_lshrrev_b32_e32 v0, 4, v2
	v_xor_b32_e32 v0, v0, v2
	v_lshlrev_b32_e32 v0, 4, v0
	v_lshlrev_b32_e32 v4, 7, v4
	v_bfe_u32 v3, v2, 4, 2
	v_lshlrev_b32_e32 v7, 7, v221
	v_and_b32_e32 v0, 0x70, v0
	v_readlane_b32 s0, v252, 29
	s_waitcnt vmcnt(6)
	v_lshl_or_b32 v8, v6, 13, v4
	v_lshl_or_b32 v4, v5, 13, v4
	v_bfe_u32 v10, v2, 1, 3
	v_add3_u32 v223, s0, v7, v0
	v_add_u32_e32 v9, s0, v4
	v_xor_b32_e32 v11, v3, v10
	v_bitop3_b32 v3, v3, v10, 4 bitop3:0x36
	v_readlane_b32 s0, v252, 30
	v_add3_u32 v222, 16, v7, v0
	v_lshlrev_b32_e32 v10, 4, v11
	v_lshlrev_b32_e32 v3, 4, v3
	v_add3_u32 v228, s0, v7, v0
	v_add_u32_e32 v0, s0, v4
	v_add_u32_e32 v8, 16, v8
	v_add_u32_e32 v229, v0, v10
	v_add_u32_e32 v230, v0, v3
	v_and_b32_e32 v0, 7, v2
	v_readlane_b32 s16, v252, 33
	s_mov_b32 s24, 0x23000
	s_mov_b32 s23, 0x13000
	v_and_b32_e32 v220, 63, v2
	v_add_u32_e32 v224, v8, v10
	v_add_u32_e32 v225, v9, v10
	v_add_u32_e32 v226, v8, v3
	v_add_u32_e32 v227, v9, v3
	v_lshlrev_b32_e32 v231, 6, v6
	v_lshlrev_b32_e32 v232, 6, v5
	v_lshlrev_b32_e32 v174, 4, v0
	v_mov_b32_e32 v175, v1
	s_mov_b64 s[0:1], 0
	v_readlane_b32 s10, v253, 22
	v_readlane_b32 s11, v253, 23
	s_mov_b32 s12, s62
	v_readlane_b32 s14, v252, 28
	v_readlane_b32 s17, v252, 34
	v_readlane_b32 s15, v253, 9
	v_readlane_b32 s21, v253, 28
	s_mov_b32 s22, 0xffff0000
	s_movk_i32 s25, 0x90
	s_mov_b32 s26, 0xc2fc0000
	s_mov_b32 s56, 0x1000000
	s_mov_b32 s57, 0x1009000
	s_mov_b32 s58, 0x1011000
	s_mov_b32 s59, 0x1019000
	s_mov_b64 s[62:63], 0x20080
	s_mov_b32 s98, 0
	v_writelane_b32 v250, s98, 5
	s_mov_b32 s98, 0x18000
	s_nop 0
	v_writelane_b32 v250, s98, 6
	s_branch .LBB0_1036

.Lswz_d1:
	v_add_u32_e32 v50, s9, v221
	v_add_u32_e32 v52, s8, v221
	v_ashrrev_i32_e32 v51, 31, v50
	v_ashrrev_i32_e32 v53, 31, v52
	v_lshlrev_b64 v[50:51], 11, v[50:51]
	v_lshlrev_b64 v[52:53], 11, v[52:53]
	v_lshl_add_u64 v[50:51], v[168:169], 0, v[50:51]
	v_lshl_add_u64 v[52:53], v[172:173], 0, v[52:53]
	v_writelane_b32 v250, s0, 4
	s_and_b64 vcc, exec, s[0:1]
	s_cbranch_vccnz .LBB0_1038
	v_add_co_u32_e32 v6, vcc, 0x20000, v50
	s_nop 1
	v_addc_co_u32_e32 v7, vcc, 0, v51, vcc
	v_add_co_u32_e32 v10, vcc, 0x40000, v50
	s_nop 1
	v_addc_co_u32_e32 v11, vcc, 0, v51, vcc
	v_add_co_u32_e32 v14, vcc, 0x60000, v50
	s_nop 1
	v_addc_co_u32_e32 v15, vcc, 0, v51, vcc
	v_add_co_u32_e32 v26, vcc, 0x20000, v52
	s_nop 1
	v_addc_co_u32_e32 v27, vcc, 0, v53, vcc
	s_nop 0
	s_nop 0
	s_nop 0
	s_nop 0
	s_nop 0
	s_nop 0
	s_nop 0
.LBB0_1038:
	v_add_co_u32_e32 v22, vcc, s79, v52
	s_mov_b32 s0, s8
	s_nop 0
	v_addc_co_u32_e32 v23, vcc, 0, v53, vcc
	v_add_co_u32_e32 v34, vcc, 0x60000, v50
	s_nop 0
	v_addc_co_u32_e32 v35, vcc, 0, v51, vcc
	v_add_co_u32_e32 v34, vcc, 0x40000, v50
	v_add_u32_e32 v54, s0, v221
	s_nop 0
	v_addc_co_u32_e32 v35, vcc, 0, v51, vcc
	v_add_co_u32_e32 v38, vcc, 0x20000, v50
	s_nop 0
	v_addc_co_u32_e32 v39, vcc, 0, v51, vcc
	s_nop 0
	s_mov_b32 s0, s9
	s_add_i32 s12, s12, s51
	s_cmp_ge_i32 s12, s15
	v_ashrrev_i32_e32 v55, 31, v54
	s_cselect_b64 s[6:7], -1, 0
	s_add_i32 s4, s12, s14
	v_lshlrev_b64 v[54:55], 11, v[54:55]
	s_cmp_lt_i32 s12, s15
	v_lshl_add_u64 v[176:177], s[76:77], 0, v[54:55]
	v_add_u32_e32 v54, s0, v221
	s_cselect_b64 s[0:1], -1, 0
	s_and_b64 s[2:3], s[0:1], exec
	s_cselect_b32 s2, s4, 0
	v_ashrrev_i32_e32 v55, 31, v54
	s_mov_b32 s100, s2
	s_lshr_b32 s98, s100, 8
	s_lshl_b32 s98, s98, 10
	s_and_b32 s99, s100, 3
	s_lshl_b32 s99, s99, 8
	s_or_b32 s3, s98, s99
	s_lshl_b32 s98, s100, 5
	s_and_b32 s2, s98, 0x1f80
	s_cmp_lt_u32 s100, 0x800
	s_cbranch_scc1 .Lswz_d3
	s_mov_b32 s3, 0x2000
	s_lshl_b32 s98, s100, 7
	s_and_b32 s2, s98, 0x1f80
.Lswz_d3:
	s_lshl_b32 s98, s3, 11
	s_add_u32 s98, s76, s98
	s_addc_u32 s99, s77, 0
	s_add_u32 s98, s98, 0x2800000
	s_addc_u32 s99, s99, 0
	s_lshl_b32 s100, s2, 11
	s_add_u32 s100, s76, s100
	s_addc_u32 s101, s77, 0
	s_add_u32 s100, s100, 0x400000
	s_addc_u32 s101, s101, 0
	v_writelane_b32 v250, s98, 0
	v_writelane_b32 v250, s99, 1
	v_writelane_b32 v250, s100, 2
	v_writelane_b32 v250, s101, 3
	v_lshlrev_b64 v[54:55], 11, v[54:55]
	v_lshl_add_u64 v[178:179], s[76:77], 0, v[54:55]
	v_add_u32_e32 v54, s3, v221
	v_ashrrev_i32_e32 v55, 31, v54
	v_lshlrev_b64 v[54:55], 11, v[54:55]
	v_add_u32_e32 v56, s2, v221
	v_lshl_add_u64 v[180:181], v[168:169], 0, v[54:55]
	s_mov_b64 s[2:3], 0x40080
	v_ashrrev_i32_e32 v57, 31, v56
	v_lshl_add_u64 v[186:187], v[180:181], 0, s[2:3]
	s_mov_b64 s[2:3], 0x60080
	v_lshlrev_b64 v[56:57], 11, v[56:57]
	v_lshl_add_u64 v[188:189], v[180:181], 0, s[2:3]
	s_mov_b64 s[2:3], 0x40000
	v_lshl_add_u64 v[182:183], v[172:173], 0, v[56:57]
	s_mov_b64 s[4:5], 0x20000
	v_lshl_add_u64 v[194:195], v[180:181], 0, s[2:3]
	s_mov_b64 s[2:3], 0x60000
	v_mov_b32_e32 v50, 0
	s_mov_b32 s13, 0
	v_lshl_add_u64 v[184:185], v[180:181], 0, s[62:63]
	v_lshl_add_u64 v[190:191], v[182:183], 0, s[62:63]
	v_lshl_add_u64 v[192:193], v[180:181], 0, s[4:5]
	v_lshl_add_u64 v[196:197], v[180:181], 0, s[2:3]
	s_mov_b64 s[64:65], 0x20000
	v_lshl_add_u64 v[198:199], v[182:183], 0, s[4:5]
	v_mov_b32_e32 v51, v50
	v_mov_b32_e32 v52, v50
	v_mov_b32_e32 v53, v50
	v_mov_b32_e32 v54, v50
	v_mov_b32_e32 v55, v50
	v_mov_b32_e32 v56, v50
	v_mov_b32_e32 v57, v50
	v_mov_b32_e32 v82, v50
	v_mov_b32_e32 v83, v50
	v_mov_b32_e32 v84, v50
	v_mov_b32_e32 v85, v50
	v_mov_b32_e32 v86, v50
	v_mov_b32_e32 v87, v50
	v_mov_b32_e32 v88, v50
	v_mov_b32_e32 v89, v50
	v_mov_b32_e32 v58, v50
	v_mov_b32_e32 v59, v50
	v_mov_b32_e32 v60, v50
	v_mov_b32_e32 v61, v50
	v_mov_b32_e32 v62, v50
	v_mov_b32_e32 v63, v50
	v_mov_b32_e32 v64, v50
	v_mov_b32_e32 v65, v50
	v_mov_b32_e32 v90, v50
	v_mov_b32_e32 v91, v50
	v_mov_b32_e32 v92, v50
	v_mov_b32_e32 v93, v50
	v_mov_b32_e32 v94, v50
	v_mov_b32_e32 v95, v50
	v_mov_b32_e32 v96, v50
	v_mov_b32_e32 v97, v50
	v_mov_b32_e32 v66, v50
	v_mov_b32_e32 v67, v50
	v_mov_b32_e32 v68, v50
	v_mov_b32_e32 v69, v50
	v_mov_b32_e32 v70, v50
	v_mov_b32_e32 v71, v50
	v_mov_b32_e32 v72, v50
	v_mov_b32_e32 v73, v50
	v_mov_b32_e32 v98, v50
	v_mov_b32_e32 v99, v50
	v_mov_b32_e32 v100, v50
	v_mov_b32_e32 v101, v50
	v_mov_b32_e32 v102, v50
	v_mov_b32_e32 v103, v50
	v_mov_b32_e32 v104, v50
	v_mov_b32_e32 v105, v50
	v_mov_b32_e32 v74, v50
	v_mov_b32_e32 v75, v50
	v_mov_b32_e32 v76, v50
	v_mov_b32_e32 v77, v50
	v_mov_b32_e32 v78, v50
	v_mov_b32_e32 v79, v50
	v_mov_b32_e32 v80, v50
	v_mov_b32_e32 v81, v50
	v_mov_b32_e32 v106, v50
	v_mov_b32_e32 v107, v50
	v_mov_b32_e32 v108, v50
	v_mov_b32_e32 v109, v50
	v_mov_b32_e32 v110, v50
	v_mov_b32_e32 v111, v50
	v_mov_b32_e32 v112, v50
	v_mov_b32_e32 v113, v50
	v_lshrrev_b32_e32 v7, 1, v221
	v_lshrrev_b32_e32 v6, 4, v174
	v_xor_b32_e32 v7, v7, v6
	v_and_b32_e32 v7, 7, v7
	v_lshlrev_b32_e32 v7, 4, v7
	v_lshl_add_u32 v0, v221, 11, v7
	v_add_u32_e32 v8, 0x20000, v0
	v_add_u32_e32 v2, 0x40000, v0
	v_add_u32_e32 v3, 0x60000, v0
	v_mov_b32_e32 v4, v0
	v_add_u32_e32 v5, 0x20000, v4
	v_lshrrev_b32_e32 v6, 3, v221
	v_lshl_add_u32 v6, v6, 10, 16
	v_add_u32_e32 v10, 0xffff8000, v225
	v_add_u32_e32 v11, 0xffff8000, v227
	v_readlane_b32 vcc_hi, v250, 4
	v_readlane_b32 s2, v250, 5
	v_readlane_b32 s3, v250, 6
	s_lshl_b32 s98, s9, 11
	s_add_u32 s98, s76, s98
	s_addc_u32 s99, s77, 0
	s_add_u32 s98, s98, 0x2800000
	s_addc_u32 s99, s99, 0
	s_lshl_b32 s100, s8, 11
	s_add_u32 s100, s76, s100
	s_addc_u32 s101, s77, 0
	s_add_u32 s100, s100, 0x400000
	s_addc_u32 s101, s101, 0
	s_cmp_lg_u32 vcc_hi, 0
	s_cbranch_scc1 .Lmyd_primed
	v_readfirstlane_b32 vcc_lo, v6
	s_nop 0
	s_add_u32 vcc_lo, vcc_lo, s2
	s_mov_b32 m0, vcc_lo
	s_nop 0
	global_load_lds_dwordx4 v0, s[98:99]
	s_add_u32 m0, m0, 0x2000
	s_nop 0
	global_load_lds_dwordx4 v8, s[98:99]
	s_add_u32 m0, m0, 0x2000
	s_nop 0
	global_load_lds_dwordx4 v2, s[98:99]
	s_add_u32 m0, m0, 0x2000
	s_nop 0
	global_load_lds_dwordx4 v3, s[98:99]
	s_add_u32 m0, vcc_lo, 0x8000
	s_nop 0
	global_load_lds_dwordx4 v4, s[100:101]
	s_add_u32 m0, m0, 0x2000
	s_nop 0
	global_load_lds_dwordx4 v5, s[100:101]
	s_add_u32 s98, s98, 0x80
	s_addc_u32 s99, s99, 0
	s_add_u32 s100, s100, 0x80
	s_addc_u32 s101, s101, 0
	s_add_u32 vcc_hi, s2, 0xc000
	s_sub_u32 vcc_lo, vcc_hi, 0x24000
	s_cselect_b32 vcc_hi, vcc_hi, vcc_lo
	v_readfirstlane_b32 vcc_lo, v6
	s_nop 0
	s_add_u32 vcc_lo, vcc_lo, vcc_hi
	s_mov_b32 m0, vcc_lo
	s_nop 0
	global_load_lds_dwordx4 v0, s[98:99]
	s_add_u32 m0, m0, 0x2000
	s_nop 0
	global_load_lds_dwordx4 v8, s[98:99]
	s_add_u32 m0, m0, 0x2000
	s_nop 0
	global_load_lds_dwordx4 v2, s[98:99]
	s_add_u32 m0, m0, 0x2000
	s_nop 0
	global_load_lds_dwordx4 v3, s[98:99]
	s_add_u32 m0, vcc_lo, 0x8000
	s_nop 0
	global_load_lds_dwordx4 v4, s[100:101]
	s_add_u32 m0, m0, 0x2000
	s_nop 0
	global_load_lds_dwordx4 v5, s[100:101]
	s_add_u32 s98, s98, 0x80
	s_addc_u32 s99, s99, 0
	s_add_u32 s100, s100, 0x80
	s_addc_u32 s101, s101, 0
	s_branch .LBB0_1040

.LBB0_1040:
	v_add_u32_e32 v12, s2, v224
	v_add_u32_e32 v13, s2, v10
	v_add_u32_e32 v14, s2, v226
	v_add_u32_e32 v15, s2, v11
	v_readfirstlane_b32 vcc_lo, v6
	s_nop 0
	s_add_u32 vcc_lo, vcc_lo, s3
	s_waitcnt vmcnt(6) lgkmcnt(0)
	s_barrier
	ds_read_b128 v[114:117], v12
	ds_read_b128 v[118:121], v12 offset:2048
	ds_read_b128 v[122:125], v12 offset:4096
	ds_read_b128 v[126:129], v12 offset:6144
	ds_read_b128 v[130:133], v13
	ds_read_b128 v[134:137], v13 offset:2048
	ds_read_b128 v[138:141], v13 offset:4096
	ds_read_b128 v[142:145], v13 offset:6144
	s_mov_b32 m0, vcc_lo
	s_nop 0
	global_load_lds_dwordx4 v0, s[98:99]
	s_add_u32 m0, m0, 0x2000
	s_nop 0
	global_load_lds_dwordx4 v8, s[98:99]
	s_add_u32 m0, m0, 0x2000
	s_nop 0
	global_load_lds_dwordx4 v2, s[98:99]
	s_add_u32 m0, m0, 0x2000
	s_nop 0
	global_load_lds_dwordx4 v3, s[98:99]
	s_add_u32 m0, vcc_lo, 0x8000
	s_nop 0
	global_load_lds_dwordx4 v4, s[100:101]
	s_add_u32 m0, m0, 0x2000
	s_nop 0
	global_load_lds_dwordx4 v5, s[100:101]
	s_add_u32 s98, s98, 0x80
	s_addc_u32 s99, s99, 0
	s_add_u32 s100, s100, 0x80
	s_addc_u32 s101, s101, 0
	s_waitcnt lgkmcnt(0)
	v_mfma_f32_16x16x32_bf16 v[110:113], v[114:117], v[130:133], v[110:113]
	ds_read_b128 v[146:149], v14
	v_mfma_f32_16x16x32_bf16 v[106:109], v[114:117], v[134:137], v[106:109]
	ds_read_b128 v[150:153], v14 offset:2048
	v_mfma_f32_16x16x32_bf16 v[78:81], v[114:117], v[138:141], v[78:81]
	ds_read_b128 v[154:157], v14 offset:4096
	v_mfma_f32_16x16x32_bf16 v[74:77], v[114:117], v[142:145], v[74:77]
	ds_read_b128 v[158:161], v14 offset:6144
	v_mfma_f32_16x16x32_bf16 v[102:105], v[118:121], v[130:133], v[102:105]
	ds_read_b128 v[162:165], v15
	v_mfma_f32_16x16x32_bf16 v[98:101], v[118:121], v[134:137], v[98:101]
	ds_read_b128 v[234:237], v15 offset:2048
	v_mfma_f32_16x16x32_bf16 v[70:73], v[118:121], v[138:141], v[70:73]
	ds_read_b128 v[238:241], v15 offset:4096
	v_mfma_f32_16x16x32_bf16 v[66:69], v[118:121], v[142:145], v[66:69]
	ds_read_b128 v[242:245], v15 offset:6144
	v_mfma_f32_16x16x32_bf16 v[94:97], v[122:125], v[130:133], v[94:97]
	v_mfma_f32_16x16x32_bf16 v[90:93], v[122:125], v[134:137], v[90:93]
	v_mfma_f32_16x16x32_bf16 v[62:65], v[122:125], v[138:141], v[62:65]
	v_mfma_f32_16x16x32_bf16 v[58:61], v[122:125], v[142:145], v[58:61]
	v_mfma_f32_16x16x32_bf16 v[86:89], v[126:129], v[130:133], v[86:89]
	v_mfma_f32_16x16x32_bf16 v[82:85], v[126:129], v[134:137], v[82:85]
	v_mfma_f32_16x16x32_bf16 v[54:57], v[126:129], v[138:141], v[54:57]
	v_mfma_f32_16x16x32_bf16 v[50:53], v[126:129], v[142:145], v[50:53]
	s_mov_b32 s3, s2
	s_add_u32 s2, s2, 0xc000
	s_sub_u32 vcc_lo, s2, 0x24000
	s_cselect_b32 s2, s2, vcc_lo
	s_mov_b32 s13, 1
.Lmyd_steady:
	v_add_u32_e32 v12, s2, v224
	v_add_u32_e32 v13, s2, v10
	v_add_u32_e32 v14, s2, v226
	v_add_u32_e32 v15, s2, v11
	v_readfirstlane_b32 vcc_lo, v6
	s_nop 0
	s_add_u32 vcc_lo, vcc_lo, s3
	s_waitcnt vmcnt(6) lgkmcnt(0)
	s_barrier
	v_mfma_f32_16x16x32_bf16 v[110:113], v[146:149], v[162:165], v[110:113]
	ds_read_b128 v[114:117], v12
	v_mfma_f32_16x16x32_bf16 v[106:109], v[146:149], v[234:237], v[106:109]
	ds_read_b128 v[118:121], v12 offset:2048
	v_mfma_f32_16x16x32_bf16 v[78:81], v[146:149], v[238:241], v[78:81]
	ds_read_b128 v[122:125], v12 offset:4096
	s_mov_b32 m0, vcc_lo
	v_mfma_f32_16x16x32_bf16 v[74:77], v[146:149], v[242:245], v[74:77]
	ds_read_b128 v[126:129], v12 offset:6144
	global_load_lds_dwordx4 v0, s[98:99]
	s_add_u32 m0, m0, 0x2000
	v_mfma_f32_16x16x32_bf16 v[102:105], v[150:153], v[162:165], v[102:105]
	ds_read_b128 v[130:133], v13
	global_load_lds_dwordx4 v8, s[98:99]
	s_add_u32 m0, m0, 0x2000
	v_mfma_f32_16x16x32_bf16 v[98:101], v[150:153], v[234:237], v[98:101]
	ds_read_b128 v[134:137], v13 offset:2048
	global_load_lds_dwordx4 v2, s[98:99]
	s_add_u32 m0, m0, 0x2000
	v_mfma_f32_16x16x32_bf16 v[70:73], v[150:153], v[238:241], v[70:73]
	ds_read_b128 v[138:141], v13 offset:4096
	global_load_lds_dwordx4 v3, s[98:99]
	s_add_u32 m0, vcc_lo, 0x8000
	v_mfma_f32_16x16x32_bf16 v[66:69], v[150:153], v[242:245], v[66:69]
	ds_read_b128 v[142:145], v13 offset:6144
	global_load_lds_dwordx4 v4, s[100:101]
	s_add_u32 m0, m0, 0x2000
	v_mfma_f32_16x16x32_bf16 v[94:97], v[154:157], v[162:165], v[94:97]
	global_load_lds_dwordx4 v5, s[100:101]
	v_mfma_f32_16x16x32_bf16 v[90:93], v[154:157], v[234:237], v[90:93]
	s_add_u32 s98, s98, 0x80
	s_addc_u32 s99, s99, 0
	s_add_u32 s100, s100, 0x80
	s_addc_u32 s101, s101, 0
	v_mfma_f32_16x16x32_bf16 v[62:65], v[154:157], v[238:241], v[62:65]
	v_mfma_f32_16x16x32_bf16 v[58:61], v[154:157], v[242:245], v[58:61]
	v_mfma_f32_16x16x32_bf16 v[86:89], v[158:161], v[162:165], v[86:89]
	v_mfma_f32_16x16x32_bf16 v[82:85], v[158:161], v[234:237], v[82:85]
	v_mfma_f32_16x16x32_bf16 v[54:57], v[158:161], v[238:241], v[54:57]
	v_mfma_f32_16x16x32_bf16 v[50:53], v[158:161], v[242:245], v[50:53]
	s_waitcnt lgkmcnt(0)
	v_mfma_f32_16x16x32_bf16 v[110:113], v[114:117], v[130:133], v[110:113]
	ds_read_b128 v[146:149], v14
	v_mfma_f32_16x16x32_bf16 v[106:109], v[114:117], v[134:137], v[106:109]
	ds_read_b128 v[150:153], v14 offset:2048
	v_mfma_f32_16x16x32_bf16 v[78:81], v[114:117], v[138:141], v[78:81]
	ds_read_b128 v[154:157], v14 offset:4096
	v_mfma_f32_16x16x32_bf16 v[74:77], v[114:117], v[142:145], v[74:77]
	ds_read_b128 v[158:161], v14 offset:6144
	v_mfma_f32_16x16x32_bf16 v[102:105], v[118:121], v[130:133], v[102:105]
	ds_read_b128 v[162:165], v15
	v_mfma_f32_16x16x32_bf16 v[98:101], v[118:121], v[134:137], v[98:101]
	ds_read_b128 v[234:237], v15 offset:2048
	v_mfma_f32_16x16x32_bf16 v[70:73], v[118:121], v[138:141], v[70:73]
	ds_read_b128 v[238:241], v15 offset:4096
	v_mfma_f32_16x16x32_bf16 v[66:69], v[118:121], v[142:145], v[66:69]
	ds_read_b128 v[242:245], v15 offset:6144
	v_mfma_f32_16x16x32_bf16 v[94:97], v[122:125], v[130:133], v[94:97]
	v_mfma_f32_16x16x32_bf16 v[90:93], v[122:125], v[134:137], v[90:93]
	v_mfma_f32_16x16x32_bf16 v[62:65], v[122:125], v[138:141], v[62:65]
	v_mfma_f32_16x16x32_bf16 v[58:61], v[122:125], v[142:145], v[58:61]
	v_mfma_f32_16x16x32_bf16 v[86:89], v[126:129], v[130:133], v[86:89]
	v_mfma_f32_16x16x32_bf16 v[82:85], v[126:129], v[134:137], v[82:85]
	v_mfma_f32_16x16x32_bf16 v[54:57], v[126:129], v[138:141], v[54:57]
	v_mfma_f32_16x16x32_bf16 v[50:53], v[126:129], v[142:145], v[50:53]
	s_mov_b32 s3, s2
	s_add_u32 s2, s2, 0xc000
	s_sub_u32 vcc_lo, s2, 0x24000
	s_cselect_b32 s2, s2, vcc_lo
	s_add_i32 s13, s13, 1
	s_cmp_lt_u32 s13, 14
	s_cbranch_scc1 .Lmyd_steady
	s_andn2_b64 vcc, exec, s[0:1]
	s_cbranch_vccnz .Lmyd_prelast_n
	v_readlane_b32 s98, v250, 0
	v_readlane_b32 s99, v250, 1
	v_readlane_b32 s100, v250, 2
	v_readlane_b32 s101, v250, 3
	v_add_u32_e32 v12, s2, v224
	v_add_u32_e32 v13, s2, v10
	v_add_u32_e32 v14, s2, v226
	v_add_u32_e32 v15, s2, v11
	v_readfirstlane_b32 vcc_lo, v6
	s_nop 0
	s_add_u32 vcc_lo, vcc_lo, s3
	s_waitcnt vmcnt(6) lgkmcnt(0)
	s_barrier
	v_mfma_f32_16x16x32_bf16 v[110:113], v[146:149], v[162:165], v[110:113]
	ds_read_b128 v[114:117], v12
	v_mfma_f32_16x16x32_bf16 v[106:109], v[146:149], v[234:237], v[106:109]
	ds_read_b128 v[118:121], v12 offset:2048
	v_mfma_f32_16x16x32_bf16 v[78:81], v[146:149], v[238:241], v[78:81]
	ds_read_b128 v[122:125], v12 offset:4096
	s_mov_b32 m0, vcc_lo
	v_mfma_f32_16x16x32_bf16 v[74:77], v[146:149], v[242:245], v[74:77]
	ds_read_b128 v[126:129], v12 offset:6144
	global_load_lds_dwordx4 v0, s[98:99]
	s_add_u32 m0, m0, 0x2000
	v_mfma_f32_16x16x32_bf16 v[102:105], v[150:153], v[162:165], v[102:105]
	ds_read_b128 v[130:133], v13
	global_load_lds_dwordx4 v8, s[98:99]
	s_add_u32 m0, m0, 0x2000
	v_mfma_f32_16x16x32_bf16 v[98:101], v[150:153], v[234:237], v[98:101]
	ds_read_b128 v[134:137], v13 offset:2048
	global_load_lds_dwordx4 v2, s[98:99]
	s_add_u32 m0, m0, 0x2000
	v_mfma_f32_16x16x32_bf16 v[70:73], v[150:153], v[238:241], v[70:73]
	ds_read_b128 v[138:141], v13 offset:4096
	global_load_lds_dwordx4 v3, s[98:99]
	s_add_u32 m0, vcc_lo, 0x8000
	v_mfma_f32_16x16x32_bf16 v[66:69], v[150:153], v[242:245], v[66:69]
	ds_read_b128 v[142:145], v13 offset:6144
	global_load_lds_dwordx4 v4, s[100:101]
	s_add_u32 m0, m0, 0x2000
	v_mfma_f32_16x16x32_bf16 v[94:97], v[154:157], v[162:165], v[94:97]
	global_load_lds_dwordx4 v5, s[100:101]
	v_mfma_f32_16x16x32_bf16 v[90:93], v[154:157], v[234:237], v[90:93]
	s_add_u32 s98, s98, 0x80
	s_addc_u32 s99, s99, 0
	s_add_u32 s100, s100, 0x80
	s_addc_u32 s101, s101, 0
	v_mfma_f32_16x16x32_bf16 v[62:65], v[154:157], v[238:241], v[62:65]
	v_mfma_f32_16x16x32_bf16 v[58:61], v[154:157], v[242:245], v[58:61]
	v_mfma_f32_16x16x32_bf16 v[86:89], v[158:161], v[162:165], v[86:89]
	v_mfma_f32_16x16x32_bf16 v[82:85], v[158:161], v[234:237], v[82:85]
	v_mfma_f32_16x16x32_bf16 v[54:57], v[158:161], v[238:241], v[54:57]
	v_mfma_f32_16x16x32_bf16 v[50:53], v[158:161], v[242:245], v[50:53]
	s_waitcnt lgkmcnt(0)
	v_mfma_f32_16x16x32_bf16 v[110:113], v[114:117], v[130:133], v[110:113]
	ds_read_b128 v[146:149], v14
	v_mfma_f32_16x16x32_bf16 v[106:109], v[114:117], v[134:137], v[106:109]
	ds_read_b128 v[150:153], v14 offset:2048
	v_mfma_f32_16x16x32_bf16 v[78:81], v[114:117], v[138:141], v[78:81]
	ds_read_b128 v[154:157], v14 offset:4096
	v_mfma_f32_16x16x32_bf16 v[74:77], v[114:117], v[142:145], v[74:77]
	ds_read_b128 v[158:161], v14 offset:6144
	v_mfma_f32_16x16x32_bf16 v[102:105], v[118:121], v[130:133], v[102:105]
	ds_read_b128 v[162:165], v15
	v_mfma_f32_16x16x32_bf16 v[98:101], v[118:121], v[134:137], v[98:101]
	ds_read_b128 v[234:237], v15 offset:2048
	v_mfma_f32_16x16x32_bf16 v[70:73], v[118:121], v[138:141], v[70:73]
	ds_read_b128 v[238:241], v15 offset:4096
	v_mfma_f32_16x16x32_bf16 v[66:69], v[118:121], v[142:145], v[66:69]
	ds_read_b128 v[242:245], v15 offset:6144
	v_mfma_f32_16x16x32_bf16 v[94:97], v[122:125], v[130:133], v[94:97]
	v_mfma_f32_16x16x32_bf16 v[90:93], v[122:125], v[134:137], v[90:93]
	v_mfma_f32_16x16x32_bf16 v[62:65], v[122:125], v[138:141], v[62:65]
	v_mfma_f32_16x16x32_bf16 v[58:61], v[122:125], v[142:145], v[58:61]
	v_mfma_f32_16x16x32_bf16 v[86:89], v[126:129], v[130:133], v[86:89]
	v_mfma_f32_16x16x32_bf16 v[82:85], v[126:129], v[134:137], v[82:85]
	v_mfma_f32_16x16x32_bf16 v[54:57], v[126:129], v[138:141], v[54:57]
	v_mfma_f32_16x16x32_bf16 v[50:53], v[126:129], v[142:145], v[50:53]
	s_mov_b32 s3, s2
	s_add_u32 s2, s2, 0xc000
	s_sub_u32 vcc_lo, s2, 0x24000
	s_cselect_b32 s2, s2, vcc_lo
	v_add_u32_e32 v12, s2, v224
	v_add_u32_e32 v13, s2, v10
	v_add_u32_e32 v14, s2, v226
	v_add_u32_e32 v15, s2, v11
	v_readfirstlane_b32 vcc_lo, v6
	s_nop 0
	s_add_u32 vcc_lo, vcc_lo, s3
	s_waitcnt vmcnt(6) lgkmcnt(0)
	s_barrier
	v_mfma_f32_16x16x32_bf16 v[110:113], v[146:149], v[162:165], v[110:113]
	ds_read_b128 v[114:117], v12
	v_mfma_f32_16x16x32_bf16 v[106:109], v[146:149], v[234:237], v[106:109]
	ds_read_b128 v[118:121], v12 offset:2048
	v_mfma_f32_16x16x32_bf16 v[78:81], v[146:149], v[238:241], v[78:81]
	ds_read_b128 v[122:125], v12 offset:4096
	s_mov_b32 m0, vcc_lo
	v_mfma_f32_16x16x32_bf16 v[74:77], v[146:149], v[242:245], v[74:77]
	ds_read_b128 v[126:129], v12 offset:6144
	global_load_lds_dwordx4 v0, s[98:99]
	s_add_u32 m0, m0, 0x2000
	v_mfma_f32_16x16x32_bf16 v[102:105], v[150:153], v[162:165], v[102:105]
	ds_read_b128 v[130:133], v13
	global_load_lds_dwordx4 v8, s[98:99]
	s_add_u32 m0, m0, 0x2000
	v_mfma_f32_16x16x32_bf16 v[98:101], v[150:153], v[234:237], v[98:101]
	ds_read_b128 v[134:137], v13 offset:2048
	global_load_lds_dwordx4 v2, s[98:99]
	s_add_u32 m0, m0, 0x2000
	v_mfma_f32_16x16x32_bf16 v[70:73], v[150:153], v[238:241], v[70:73]
	ds_read_b128 v[138:141], v13 offset:4096
	global_load_lds_dwordx4 v3, s[98:99]
	s_add_u32 m0, vcc_lo, 0x8000
	v_mfma_f32_16x16x32_bf16 v[66:69], v[150:153], v[242:245], v[66:69]
	ds_read_b128 v[142:145], v13 offset:6144
	global_load_lds_dwordx4 v4, s[100:101]
	s_add_u32 m0, m0, 0x2000
	v_mfma_f32_16x16x32_bf16 v[94:97], v[154:157], v[162:165], v[94:97]
	global_load_lds_dwordx4 v5, s[100:101]
	v_mfma_f32_16x16x32_bf16 v[90:93], v[154:157], v[234:237], v[90:93]
	s_add_u32 s98, s98, 0x80
	s_addc_u32 s99, s99, 0
	s_add_u32 s100, s100, 0x80
	s_addc_u32 s101, s101, 0
	v_mfma_f32_16x16x32_bf16 v[62:65], v[154:157], v[238:241], v[62:65]
	v_mfma_f32_16x16x32_bf16 v[58:61], v[154:157], v[242:245], v[58:61]
	v_mfma_f32_16x16x32_bf16 v[86:89], v[158:161], v[162:165], v[86:89]
	v_mfma_f32_16x16x32_bf16 v[82:85], v[158:161], v[234:237], v[82:85]
	v_mfma_f32_16x16x32_bf16 v[54:57], v[158:161], v[238:241], v[54:57]
	v_mfma_f32_16x16x32_bf16 v[50:53], v[158:161], v[242:245], v[50:53]
	s_waitcnt lgkmcnt(0)
	v_mfma_f32_16x16x32_bf16 v[110:113], v[114:117], v[130:133], v[110:113]
	ds_read_b128 v[146:149], v14
	v_mfma_f32_16x16x32_bf16 v[106:109], v[114:117], v[134:137], v[106:109]
	ds_read_b128 v[150:153], v14 offset:2048
	v_mfma_f32_16x16x32_bf16 v[78:81], v[114:117], v[138:141], v[78:81]
	ds_read_b128 v[154:157], v14 offset:4096
	v_mfma_f32_16x16x32_bf16 v[74:77], v[114:117], v[142:145], v[74:77]
	ds_read_b128 v[158:161], v14 offset:6144
	v_mfma_f32_16x16x32_bf16 v[102:105], v[118:121], v[130:133], v[102:105]
	ds_read_b128 v[162:165], v15
	v_mfma_f32_16x16x32_bf16 v[98:101], v[118:121], v[134:137], v[98:101]
	ds_read_b128 v[234:237], v15 offset:2048
	v_mfma_f32_16x16x32_bf16 v[70:73], v[118:121], v[138:141], v[70:73]
	ds_read_b128 v[238:241], v15 offset:4096
	v_mfma_f32_16x16x32_bf16 v[66:69], v[118:121], v[142:145], v[66:69]
	ds_read_b128 v[242:245], v15 offset:6144
	v_mfma_f32_16x16x32_bf16 v[94:97], v[122:125], v[130:133], v[94:97]
	v_mfma_f32_16x16x32_bf16 v[90:93], v[122:125], v[134:137], v[90:93]
	v_mfma_f32_16x16x32_bf16 v[62:65], v[122:125], v[138:141], v[62:65]
	v_mfma_f32_16x16x32_bf16 v[58:61], v[122:125], v[142:145], v[58:61]
	v_mfma_f32_16x16x32_bf16 v[86:89], v[126:129], v[130:133], v[86:89]
	v_mfma_f32_16x16x32_bf16 v[82:85], v[126:129], v[134:137], v[82:85]
	v_mfma_f32_16x16x32_bf16 v[54:57], v[126:129], v[138:141], v[54:57]
	v_mfma_f32_16x16x32_bf16 v[50:53], v[126:129], v[142:145], v[50:53]
	s_mov_b32 s3, s2
	s_add_u32 s2, s2, 0xc000
	s_sub_u32 vcc_lo, s2, 0x24000
	s_cselect_b32 s2, s2, vcc_lo
	s_waitcnt lgkmcnt(0)
	s_barrier
	v_readlane_b32 vcc_lo, v250, 7
	s_nop 0
	s_add_u32 vcc_lo, vcc_lo, s3
	s_sub_u32 vcc_lo, vcc_lo, 0x18000
	v_mov_b32_e32 v202, vcc_lo
	v_mfma_f32_16x16x32_bf16 v[110:113], v[146:149], v[162:165], v[110:113]
	v_mfma_f32_16x16x32_bf16 v[106:109], v[146:149], v[234:237], v[106:109]
	v_mfma_f32_16x16x32_bf16 v[78:81], v[146:149], v[238:241], v[78:81]
	v_mfma_f32_16x16x32_bf16 v[74:77], v[146:149], v[242:245], v[74:77]
	v_mfma_f32_16x16x32_bf16 v[102:105], v[150:153], v[162:165], v[102:105]
	v_mfma_f32_16x16x32_bf16 v[98:101], v[150:153], v[234:237], v[98:101]
	v_mfma_f32_16x16x32_bf16 v[70:73], v[150:153], v[238:241], v[70:73]
	v_mfma_f32_16x16x32_bf16 v[66:69], v[150:153], v[242:245], v[66:69]
	v_mfma_f32_16x16x32_bf16 v[94:97], v[154:157], v[162:165], v[94:97]
	v_mfma_f32_16x16x32_bf16 v[90:93], v[154:157], v[234:237], v[90:93]
	v_mfma_f32_16x16x32_bf16 v[62:65], v[154:157], v[238:241], v[62:65]
	v_mfma_f32_16x16x32_bf16 v[58:61], v[154:157], v[242:245], v[58:61]
	v_mfma_f32_16x16x32_bf16 v[86:89], v[158:161], v[162:165], v[86:89]
	v_mfma_f32_16x16x32_bf16 v[82:85], v[158:161], v[234:237], v[82:85]
	v_mfma_f32_16x16x32_bf16 v[54:57], v[158:161], v[238:241], v[54:57]
	v_mfma_f32_16x16x32_bf16 v[50:53], v[158:161], v[242:245], v[50:53]
	v_writelane_b32 v250, s2, 5
	v_writelane_b32 v250, s3, 6
	s_and_b64 vcc, exec, s[2:3]
	s_nop 7
	s_branch .LBB0_1053
.Lmyd_prelast_n:
	v_add_u32_e32 v12, s2, v224
	v_add_u32_e32 v13, s2, v10
	v_add_u32_e32 v14, s2, v226
	v_add_u32_e32 v15, s2, v11
	s_waitcnt vmcnt(6) lgkmcnt(0)
	s_barrier
	v_mfma_f32_16x16x32_bf16 v[110:113], v[146:149], v[162:165], v[110:113]
	ds_read_b128 v[114:117], v12
	v_mfma_f32_16x16x32_bf16 v[106:109], v[146:149], v[234:237], v[106:109]
	ds_read_b128 v[118:121], v12 offset:2048
	v_mfma_f32_16x16x32_bf16 v[78:81], v[146:149], v[238:241], v[78:81]
	ds_read_b128 v[122:125], v12 offset:4096
	v_mfma_f32_16x16x32_bf16 v[74:77], v[146:149], v[242:245], v[74:77]
	ds_read_b128 v[126:129], v12 offset:6144
	v_mfma_f32_16x16x32_bf16 v[102:105], v[150:153], v[162:165], v[102:105]
	ds_read_b128 v[130:133], v13
	v_mfma_f32_16x16x32_bf16 v[98:101], v[150:153], v[234:237], v[98:101]
	ds_read_b128 v[134:137], v13 offset:2048
	v_mfma_f32_16x16x32_bf16 v[70:73], v[150:153], v[238:241], v[70:73]
	ds_read_b128 v[138:141], v13 offset:4096
	v_mfma_f32_16x16x32_bf16 v[66:69], v[150:153], v[242:245], v[66:69]
	ds_read_b128 v[142:145], v13 offset:6144
	v_mfma_f32_16x16x32_bf16 v[94:97], v[154:157], v[162:165], v[94:97]
	v_mfma_f32_16x16x32_bf16 v[90:93], v[154:157], v[234:237], v[90:93]
	v_mfma_f32_16x16x32_bf16 v[62:65], v[154:157], v[238:241], v[62:65]
	v_mfma_f32_16x16x32_bf16 v[58:61], v[154:157], v[242:245], v[58:61]
	v_mfma_f32_16x16x32_bf16 v[86:89], v[158:161], v[162:165], v[86:89]
	v_mfma_f32_16x16x32_bf16 v[82:85], v[158:161], v[234:237], v[82:85]
	v_mfma_f32_16x16x32_bf16 v[54:57], v[158:161], v[238:241], v[54:57]
	v_mfma_f32_16x16x32_bf16 v[50:53], v[158:161], v[242:245], v[50:53]
	s_waitcnt lgkmcnt(0)
	v_mfma_f32_16x16x32_bf16 v[110:113], v[114:117], v[130:133], v[110:113]
	ds_read_b128 v[146:149], v14
	v_mfma_f32_16x16x32_bf16 v[106:109], v[114:117], v[134:137], v[106:109]
	ds_read_b128 v[150:153], v14 offset:2048
	v_mfma_f32_16x16x32_bf16 v[78:81], v[114:117], v[138:141], v[78:81]
	ds_read_b128 v[154:157], v14 offset:4096
	v_mfma_f32_16x16x32_bf16 v[74:77], v[114:117], v[142:145], v[74:77]
	ds_read_b128 v[158:161], v14 offset:6144
	v_mfma_f32_16x16x32_bf16 v[102:105], v[118:121], v[130:133], v[102:105]
	ds_read_b128 v[162:165], v15
	v_mfma_f32_16x16x32_bf16 v[98:101], v[118:121], v[134:137], v[98:101]
	ds_read_b128 v[234:237], v15 offset:2048
	v_mfma_f32_16x16x32_bf16 v[70:73], v[118:121], v[138:141], v[70:73]
	ds_read_b128 v[238:241], v15 offset:4096
	v_mfma_f32_16x16x32_bf16 v[66:69], v[118:121], v[142:145], v[66:69]
	ds_read_b128 v[242:245], v15 offset:6144
	v_mfma_f32_16x16x32_bf16 v[94:97], v[122:125], v[130:133], v[94:97]
	v_mfma_f32_16x16x32_bf16 v[90:93], v[122:125], v[134:137], v[90:93]
	v_mfma_f32_16x16x32_bf16 v[62:65], v[122:125], v[138:141], v[62:65]
	v_mfma_f32_16x16x32_bf16 v[58:61], v[122:125], v[142:145], v[58:61]
	v_mfma_f32_16x16x32_bf16 v[86:89], v[126:129], v[130:133], v[86:89]
	v_mfma_f32_16x16x32_bf16 v[82:85], v[126:129], v[134:137], v[82:85]
	v_mfma_f32_16x16x32_bf16 v[54:57], v[126:129], v[138:141], v[54:57]
	v_mfma_f32_16x16x32_bf16 v[50:53], v[126:129], v[142:145], v[50:53]
	s_mov_b32 s3, s2
	s_add_u32 s2, s2, 0xc000
	s_sub_u32 vcc_lo, s2, 0x24000
	s_cselect_b32 s2, s2, vcc_lo
	v_add_u32_e32 v12, s2, v224
	v_add_u32_e32 v13, s2, v10
	v_add_u32_e32 v14, s2, v226
	v_add_u32_e32 v15, s2, v11
	s_waitcnt vmcnt(0) lgkmcnt(0)
	s_barrier
	v_mfma_f32_16x16x32_bf16 v[110:113], v[146:149], v[162:165], v[110:113]
	ds_read_b128 v[114:117], v12
	v_mfma_f32_16x16x32_bf16 v[106:109], v[146:149], v[234:237], v[106:109]
	ds_read_b128 v[118:121], v12 offset:2048
	v_mfma_f32_16x16x32_bf16 v[78:81], v[146:149], v[238:241], v[78:81]
	ds_read_b128 v[122:125], v12 offset:4096
	v_mfma_f32_16x16x32_bf16 v[74:77], v[146:149], v[242:245], v[74:77]
	ds_read_b128 v[126:129], v12 offset:6144
	v_mfma_f32_16x16x32_bf16 v[102:105], v[150:153], v[162:165], v[102:105]
	ds_read_b128 v[130:133], v13
	v_mfma_f32_16x16x32_bf16 v[98:101], v[150:153], v[234:237], v[98:101]
	ds_read_b128 v[134:137], v13 offset:2048
	v_mfma_f32_16x16x32_bf16 v[70:73], v[150:153], v[238:241], v[70:73]
	ds_read_b128 v[138:141], v13 offset:4096
	v_mfma_f32_16x16x32_bf16 v[66:69], v[150:153], v[242:245], v[66:69]
	ds_read_b128 v[142:145], v13 offset:6144
	v_mfma_f32_16x16x32_bf16 v[94:97], v[154:157], v[162:165], v[94:97]
	v_mfma_f32_16x16x32_bf16 v[90:93], v[154:157], v[234:237], v[90:93]
	v_mfma_f32_16x16x32_bf16 v[62:65], v[154:157], v[238:241], v[62:65]
	v_mfma_f32_16x16x32_bf16 v[58:61], v[154:157], v[242:245], v[58:61]
	v_mfma_f32_16x16x32_bf16 v[86:89], v[158:161], v[162:165], v[86:89]
	v_mfma_f32_16x16x32_bf16 v[82:85], v[158:161], v[234:237], v[82:85]
	v_mfma_f32_16x16x32_bf16 v[54:57], v[158:161], v[238:241], v[54:57]
	v_mfma_f32_16x16x32_bf16 v[50:53], v[158:161], v[242:245], v[50:53]
	s_waitcnt lgkmcnt(0)
	v_mfma_f32_16x16x32_bf16 v[110:113], v[114:117], v[130:133], v[110:113]
	ds_read_b128 v[146:149], v14
	v_mfma_f32_16x16x32_bf16 v[106:109], v[114:117], v[134:137], v[106:109]
	ds_read_b128 v[150:153], v14 offset:2048
	v_mfma_f32_16x16x32_bf16 v[78:81], v[114:117], v[138:141], v[78:81]
	ds_read_b128 v[154:157], v14 offset:4096
	v_mfma_f32_16x16x32_bf16 v[74:77], v[114:117], v[142:145], v[74:77]
	ds_read_b128 v[158:161], v14 offset:6144
	v_mfma_f32_16x16x32_bf16 v[102:105], v[118:121], v[130:133], v[102:105]
	ds_read_b128 v[162:165], v15
	v_mfma_f32_16x16x32_bf16 v[98:101], v[118:121], v[134:137], v[98:101]
	ds_read_b128 v[234:237], v15 offset:2048
	v_mfma_f32_16x16x32_bf16 v[70:73], v[118:121], v[138:141], v[70:73]
	ds_read_b128 v[238:241], v15 offset:4096
	v_mfma_f32_16x16x32_bf16 v[66:69], v[118:121], v[142:145], v[66:69]
	ds_read_b128 v[242:245], v15 offset:6144
	v_mfma_f32_16x16x32_bf16 v[94:97], v[122:125], v[130:133], v[94:97]
	v_mfma_f32_16x16x32_bf16 v[90:93], v[122:125], v[134:137], v[90:93]
	v_mfma_f32_16x16x32_bf16 v[62:65], v[122:125], v[138:141], v[62:65]
	v_mfma_f32_16x16x32_bf16 v[58:61], v[122:125], v[142:145], v[58:61]
	v_mfma_f32_16x16x32_bf16 v[86:89], v[126:129], v[130:133], v[86:89]
	v_mfma_f32_16x16x32_bf16 v[82:85], v[126:129], v[134:137], v[82:85]
	v_mfma_f32_16x16x32_bf16 v[54:57], v[126:129], v[138:141], v[54:57]
	v_mfma_f32_16x16x32_bf16 v[50:53], v[126:129], v[142:145], v[50:53]
	s_mov_b32 s3, s2
	s_add_u32 s2, s2, 0xc000
	s_sub_u32 vcc_lo, s2, 0x24000
	s_cselect_b32 s2, s2, vcc_lo
	s_waitcnt lgkmcnt(0)
	s_barrier
	v_readlane_b32 vcc_lo, v250, 7
	s_nop 0
	s_add_u32 vcc_lo, vcc_lo, s3
	s_sub_u32 vcc_lo, vcc_lo, 0x18000
	v_mov_b32_e32 v202, vcc_lo
	v_mfma_f32_16x16x32_bf16 v[110:113], v[146:149], v[162:165], v[110:113]
	v_mfma_f32_16x16x32_bf16 v[106:109], v[146:149], v[234:237], v[106:109]
	v_mfma_f32_16x16x32_bf16 v[78:81], v[146:149], v[238:241], v[78:81]
	v_mfma_f32_16x16x32_bf16 v[74:77], v[146:149], v[242:245], v[74:77]
	v_mfma_f32_16x16x32_bf16 v[102:105], v[150:153], v[162:165], v[102:105]
	v_mfma_f32_16x16x32_bf16 v[98:101], v[150:153], v[234:237], v[98:101]
	v_mfma_f32_16x16x32_bf16 v[70:73], v[150:153], v[238:241], v[70:73]
	v_mfma_f32_16x16x32_bf16 v[66:69], v[150:153], v[242:245], v[66:69]
	v_mfma_f32_16x16x32_bf16 v[94:97], v[154:157], v[162:165], v[94:97]
	v_mfma_f32_16x16x32_bf16 v[90:93], v[154:157], v[234:237], v[90:93]
	v_mfma_f32_16x16x32_bf16 v[62:65], v[154:157], v[238:241], v[62:65]
	v_mfma_f32_16x16x32_bf16 v[58:61], v[154:157], v[242:245], v[58:61]
	v_mfma_f32_16x16x32_bf16 v[86:89], v[158:161], v[162:165], v[86:89]
	v_mfma_f32_16x16x32_bf16 v[82:85], v[158:161], v[234:237], v[82:85]
	v_mfma_f32_16x16x32_bf16 v[54:57], v[158:161], v[238:241], v[54:57]
	v_mfma_f32_16x16x32_bf16 v[50:53], v[158:161], v[242:245], v[50:53]
	v_writelane_b32 v250, s2, 5
	v_writelane_b32 v250, s3, 6
	s_and_b64 vcc, exec, s[2:3]
	s_nop 7
	s_branch .LBB0_1053
